# fused norm tail: h kept in accumulator registers, XN computed without re-reading the h tile
# speedup vs baseline: 1.0165x; 1.0165x over previous
; __device__ __forceinline__ void epi_all_run(const void* Pk_, int l, int s, const f32x4 (&acc)[2][2][4][2], const pg8::Unit& u, int wr, int wc, int fr, int fq) {
;     ...
;             const float* MOD = (const float*)(ws + WS_MOD);
;             const int gidx = (s == 1) ? 2 : (s == 4 ? 5 : 8);
;             const float* base = (l == 0 && s == 1) ? A.x : A.out; float* out = A.out;
;             const float* gp = MOD + (size_t)(l * 4 + b) * NMODC + gidx * DM; const float scale = (s == 4) ? 1.0f : 0.5f;
;             const int nsite = 3 * l + (s == 1 ? 1 : (s == 4 ? 2 : 3));
;             const int col0 = u.pn * 256 + wc * 32 + 8 * fq;
;             float* slots = (float*)(ws + WS_RSP) + (size_t)nsite * M * 16;
;             f32x4 gv[2][2];
; #pragma unroll
;             for (int bj = 0; bj < 2; ++bj)
; #pragma unroll
;                 for (int n = 0; n < 2; ++n) gv[bj][n] = *(const f32x4*)(gp + col0 + bj * 128 + n * 4) * scale;
;             f32x4 bb[2][2][2];
; #pragma unroll
;             for (int bj = 0; bj < 2; ++bj)
; #pragma unroll
;                 for (int n = 0; n < 2; ++n) bb[0][bj][n] = *(const f32x4*)(base + (size_t)row0 * DM + col0 + bj * 128 + n * 4);
; #pragma unroll
;             for (int g = 0; g < 8; ++g) {
;                 const int ai = g >> 2, m = g & 3, row = row0 + ai * 128 + m * 16;
;                 if (g < 7) { const int rown = row0 + ((g + 1) >> 2) * 128 + ((g + 1) & 3) * 16;
; #pragma unroll
;                     for (int bj = 0; bj < 2; ++bj)
; #pragma unroll
;                         for (int n = 0; n < 2; ++n) bb[(g + 1) & 1][bj][n] = *(const f32x4*)(base + (size_t)rown * DM + col0 + bj * 128 + n * 4); }
;                 float ss = 0.f;
; #pragma unroll
;                 for (int bj = 0; bj < 2; ++bj)
; #pragma unroll
;                     for (int n = 0; n < 2; ++n) {
;                         const f32x4 h = bb[g & 1][bj][n] + gv[bj][n] * acc[ai][bj][m][n];
;                         *(f32x4*)(out + (size_t)row * DM + col0 + bj * 128 + n * 4) = h;
;                         ss += (h[0] * h[0] + h[1] * h[1]) + (h[2] * h[2] + h[3] * h[3]);
;                     }
;                 if (nsite < 3 * DEPTH) {
;                     ss += shx(ss, 16); ss += shx(ss, 32);
;                     if (fq == 0) __hip_atomic_store(slots + ((size_t)u.pn * M + row) * 4 + wc, ss, __ATOMIC_RELAXED, __HIP_MEMORY_SCOPE_AGENT);
;                 }
.LBB0_90:
	s_andn2_b64 vcc, exec, s[46:47]
	v_or_b32_e32 v186, 16, v184
	s_cbranch_vccnz .LBB0_125
	s_ashr_i32 s20, s31, 4
	s_cmp_eq_u32 s75, 0
	s_cselect_b64 s[38:39], -1, 0
	s_cmp_eq_u32 s76, 4
	s_cselect_b64 s[46:47], -1, 0
	v_cndmask_b32_e64 v168, 0.5, 1.0, s[46:47]
	s_and_b64 s[46:47], s[46:47], exec
	s_cselect_b32 s31, s93, 0x2000
	s_cselect_b32 s50, 2, 3
	s_cmp_eq_u32 s76, 1
	s_cselect_b64 s[46:47], -1, 0
	s_and_b64 s[48:49], s[46:47], exec
	s_cselect_b32 s31, 0x800, s31
	s_cselect_b32 s48, 1, s50
	s_and_b64 s[38:39], s[38:39], s[46:47]
	s_and_b64 s[38:39], s[38:39], exec
	s_cselect_b32 s38, 0, 0xc0
	s_add_u32 s38, s4, s38
	s_addc_u32 s39, s5, 0
	s_lshl_b32 s46, s75, 2
	s_add_i32 s20, s46, s20
	s_mul_hi_i32 s46, s20, 0x9000
	s_mul_i32 s20, s20, 0x9000
	s_waitcnt lgkmcnt(0)
	s_add_u32 s20, s34, s20
	s_addc_u32 s47, s35, s46
	s_lshl_b32 s31, s31, 2
	v_lshl_or_b32 v130, s30, 8, v228
	s_add_u32 s46, s20, s31
	v_ashrrev_i32_e32 v131, 31, v130
	s_load_dwordx2 s[38:39], s[38:39], 0x0
	s_nop 0
	s_load_dwordx2 s[4:5], s[4:5], 0xc0
	s_addc_u32 s47, s47, 0
	v_lshlrev_b64 v[188:189], 2, v[130:131]
	v_lshl_add_u64 v[130:131], s[46:47], 0, v[188:189]
	s_mov_b64 s[46:47], 0x10000
	s_mov_b32 s20, 0x10000
	v_lshl_add_u64 v[132:133], v[130:131], 0, s[46:47]
	v_add_co_u32_e32 v130, vcc, s20, v130
	v_ashrrev_i32_e32 v185, 31, v184
	s_nop 0
	v_addc_co_u32_e32 v131, vcc, 0, v131, vcc
	v_lshlrev_b64 v[190:191], 12, v[184:185]
	v_ashrrev_i32_e32 v187, 31, v186
	global_load_dwordx4 v[142:145], v[130:131], off
	global_load_dwordx4 v[150:153], v[132:133], off offset:528
	global_load_dwordx4 v[154:157], v[132:133], off offset:16
	global_load_dwordx4 v[158:161], v[132:133], off offset:512
	s_waitcnt lgkmcnt(0)
	v_lshl_add_u64 v[130:131], s[38:39], 0, v[190:191]
	v_lshl_add_u64 v[206:207], s[38:39], 0, v[188:189]
	v_lshlrev_b64 v[166:167], 12, v[186:187]
	v_lshl_add_u64 v[130:131], v[130:131], 0, v[188:189]
	v_lshl_add_u64 v[134:135], v[206:207], 0, v[166:167]
	global_load_dwordx4 v[162:165], v[130:131], off
	global_load_dwordx4 v[208:211], v[130:131], off offset:16
	global_load_dwordx4 v[212:215], v[130:131], off offset:528
	global_load_dwordx4 v[230:233], v[130:131], off offset:512
	global_load_dwordx4 v[138:141], v[134:135], off offset:16
	global_load_dwordx4 v[146:149], v[134:135], off
	s_nop 0
	global_load_dwordx4 v[130:133], v[134:135], off offset:528
	s_nop 0
	global_load_dwordx4 v[134:137], v[134:135], off offset:512
	s_mul_i32 s75, s75, 3
	s_add_i32 s48, s48, s75
	s_ashr_i32 s49, s48, 31
	v_lshl_add_u64 v[200:201], s[4:5], 0, v[188:189]
	s_lshl_b64 s[4:5], s[48:49], 20
	s_add_u32 s4, s34, s4
	s_addc_u32 s5, s35, s5
	s_add_u32 s20, s4, 0xed00000
	s_addc_u32 s46, s5, 0
	v_lshl_add_u64 v[234:235], v[200:201], 0, v[190:191]
	s_cmp_lt_i32 s48, 6
	s_cselect_b64 s[38:39], -1, 0
	s_cmp_gt_i32 s48, 5
	s_waitcnt vmcnt(0)
	v_pk_mul_f32 v[202:203], v[168:169], v[144:145] op_sel_hi:[0,1]
	v_pk_mul_f32 v[204:205], v[168:169], v[142:143] op_sel_hi:[0,1]
	v_pk_mul_f32 v[198:199], v[168:169], v[156:157] op_sel_hi:[0,1]
	v_pk_mul_f32 v[196:197], v[168:169], v[154:155] op_sel_hi:[0,1]
	v_pk_mul_f32 v[192:193], v[168:169], v[160:161] op_sel_hi:[0,1]
	v_pk_mul_f32 v[194:195], v[168:169], v[158:159] op_sel_hi:[0,1]
	v_pk_mul_f32 v[190:191], v[168:169], v[152:153] op_sel_hi:[0,1]
	v_pk_mul_f32 v[188:189], v[168:169], v[150:151] op_sel_hi:[0,1]
	v_pk_fma_f32 v[128:129], v[128:129], v[202:203], v[164:165]
	v_pk_fma_f32 v[126:127], v[126:127], v[204:205], v[162:163]
	v_pk_fma_f32 v[124:125], v[124:125], v[198:199], v[210:211]
	v_pk_fma_f32 v[122:123], v[122:123], v[196:197], v[208:209]
	v_pk_fma_f32 v[120:121], v[120:121], v[192:193], v[232:233]
	v_pk_fma_f32 v[118:119], v[118:119], v[194:195], v[230:231]
	v_pk_fma_f32 v[116:117], v[116:117], v[190:191], v[214:215]
	v_pk_fma_f32 v[114:115], v[114:115], v[188:189], v[212:213]
	global_store_dwordx4 v[234:235], v[126:129], off
	global_store_dwordx4 v[234:235], v[122:125], off offset:16
	global_store_dwordx4 v[234:235], v[118:121], off offset:512
	global_store_dwordx4 v[234:235], v[114:117], off offset:528
	s_cbranch_scc1 .LBB0_95
	v_mul_f32_e32 v143, v127, v127
	v_fmac_f32_e32 v143, v126, v126
	v_mul_f32_e32 v142, v129, v129
	v_fmac_f32_e32 v142, v128, v128
	v_add_f32_e32 v142, v143, v142
	v_mul_f32_e32 v143, v123, v123
	v_mul_f32_e32 v144, v125, v125
	v_fmac_f32_e32 v143, v122, v122
	v_fmac_f32_e32 v144, v124, v124
	v_add_f32_e32 v143, v143, v144
	v_add_f32_e32 v142, v142, v143
	v_mul_f32_e32 v143, v119, v119
	v_mul_f32_e32 v144, v121, v121
	v_fmac_f32_e32 v143, v118, v118
	v_fmac_f32_e32 v144, v120, v120
	v_add_f32_e32 v143, v143, v144
	v_add_f32_e32 v142, v142, v143
	v_mul_f32_e32 v143, v115, v115
	v_mul_f32_e32 v144, v117, v117
	v_fmac_f32_e32 v143, v114, v114
	v_fmac_f32_e32 v144, v116, v116
	v_add_f32_e32 v143, v143, v144
	v_add_f32_e32 v142, v142, v143
	v_mov_b32_e32 v143, v179
	s_nop 0
	v_lshlrev_b32_e32 v143, 2, v143
	v_bitop3_b32 v143, v143, 64, v220 bitop3:0x6c
	ds_bpermute_b32 v143, v143, v142
	s_waitcnt lgkmcnt(0)
	v_add_f32_e32 v142, v142, v143
	v_mov_b32_e32 v143, v179
	s_nop 0
	v_lshlrev_b32_e32 v143, 2, v143
	v_bitop3_b32 v143, v143, s33, v220 bitop3:0x6c
	ds_bpermute_b32 v143, v143, v142
	s_and_saveexec_b64 s[4:5], s[42:43]
	s_cbranch_execz .LBB0_94
	s_ashr_i32 s31, s30, 31
	s_lshl_b64 s[48:49], s[30:31], 18
	s_add_u32 s48, s20, s48
	s_addc_u32 s49, s46, s49
	s_waitcnt lgkmcnt(0)
	v_add_f32_e32 v144, v142, v143
	v_lshl_add_u64 v[142:143], v[184:185], 4, s[48:49]
	v_readlane_b32 s48, v237, 58
	v_readlane_b32 s49, v237, 59
	s_lshl_b32 s48, s64, 2
	s_mov_b32 s31, s49
	v_writelane_b32 v237, s30, 58
	v_lshl_add_u64 v[142:143], v[142:143], 0, s[48:49]
	global_store_dword v[142:143], v144, off sc1
	v_writelane_b32 v237, s31, 59

; __device__ __forceinline__ float shx(float v, int o) { const int idx = (((int)otid() & 63) ^ o) << 2; return __builtin_bit_cast(float, __builtin_amdgcn_ds_bpermute(idx, __builtin_bit_cast(int, v))); }
; __device__ __forceinline__ void epi_all_run(const void* Pk_, int l, int s, const f32x4 (&acc)[2][2][4][2], const pg8::Unit& u, int wr, int wc, int fr, int fq) {
;     ...
;             for (int g = 0; g < 8; ++g) {
;                 const int ai = g >> 2, m = g & 3, row = row0 + ai * 128 + m * 16;
;                 if (g < 7) { const int rown = row0 + ((g + 1) >> 2) * 128 + ((g + 1) & 3) * 16;
; #pragma unroll
;                     for (int bj = 0; bj < 2; ++bj)
; #pragma unroll
;                         for (int n = 0; n < 2; ++n) bb[(g + 1) & 1][bj][n] = *(const f32x4*)(base + (size_t)rown * DM + col0 + bj * 128 + n * 4); }
;                 float ss = 0.f;
; #pragma unroll
;                 for (int bj = 0; bj < 2; ++bj)
; #pragma unroll
;                     for (int n = 0; n < 2; ++n) {
;                         const f32x4 h = bb[g & 1][bj][n] + gv[bj][n] * acc[ai][bj][m][n];
;                         *(f32x4*)(out + (size_t)row * DM + col0 + bj * 128 + n * 4) = h;
;                         ss += (h[0] * h[0] + h[1] * h[1]) + (h[2] * h[2] + h[3] * h[3]);
;                     }
;                 if (nsite < 3 * DEPTH) {
;                     ss += shx(ss, 16); ss += shx(ss, 32);
;                     if (fq == 0) __hip_atomic_store(slots + ((size_t)u.pn * M + row) * 4 + wc, ss, __ATOMIC_RELAXED, __HIP_MEMORY_SCOPE_AGENT);
;                 }
;             }
.LBB0_95:
	v_or_b32_e32 v208, 32, v184
	v_ashrrev_i32_e32 v209, 31, v208
	v_lshlrev_b64 v[212:213], 12, v[208:209]
	v_lshl_add_u64 v[150:151], v[206:207], 0, v[212:213]
	global_load_dwordx4 v[154:157], v[150:151], off offset:16
	global_load_dwordx4 v[162:165], v[150:151], off
	s_waitcnt lgkmcnt(0)
	global_load_dwordx4 v[142:145], v[150:151], off offset:528
	s_nop 0
	global_load_dwordx4 v[150:153], v[150:151], off offset:512
	v_cndmask_b32_e64 v160, 0, 1, s[38:39]
	v_lshl_add_u64 v[158:159], v[200:201], 0, v[166:167]
	v_pk_fma_f32 v[112:113], v[112:113], v[202:203], v[148:149]
	v_pk_fma_f32 v[110:111], v[110:111], v[204:205], v[146:147]
	v_pk_fma_f32 v[108:109], v[108:109], v[198:199], v[140:141]
	v_pk_fma_f32 v[106:107], v[106:107], v[196:197], v[138:139]
	v_pk_fma_f32 v[104:105], v[104:105], v[192:193], v[136:137]
	v_pk_fma_f32 v[102:103], v[102:103], v[194:195], v[134:135]
	v_pk_fma_f32 v[100:101], v[100:101], v[190:191], v[132:133]
	v_pk_fma_f32 v[98:99], v[98:99], v[188:189], v[130:131]
	v_cmp_ne_u32_e64 s[4:5], 1, v160
	s_andn2_b64 vcc, exec, s[38:39]
	global_store_dwordx4 v[158:159], v[110:113], off
	global_store_dwordx4 v[158:159], v[106:109], off offset:16
	global_store_dwordx4 v[158:159], v[102:105], off offset:512
	global_store_dwordx4 v[158:159], v[98:101], off offset:528
	s_cbranch_vccnz .LBB0_99
	v_mul_f32_e32 v147, v111, v111
	v_mul_f32_e32 v139, v107, v107
	v_mul_f32_e32 v131, v99, v99
	v_fmac_f32_e32 v147, v110, v110
	v_mul_f32_e32 v146, v113, v113
	v_fmac_f32_e32 v139, v106, v106
	v_mul_f32_e32 v138, v109, v109
	v_mul_f32_e32 v135, v103, v103
	v_fmac_f32_e32 v131, v98, v98
	v_mul_f32_e32 v130, v101, v101
	v_fmac_f32_e32 v146, v112, v112
	v_fmac_f32_e32 v138, v108, v108
	v_fmac_f32_e32 v135, v102, v102
	v_mul_f32_e32 v134, v105, v105
	v_fmac_f32_e32 v130, v100, v100
	v_add_f32_e32 v146, v147, v146
	v_add_f32_e32 v138, v139, v138
	v_fmac_f32_e32 v134, v104, v104
	v_add_f32_e32 v130, v131, v130
	v_mov_b32_e32 v131, v179
	v_add_f32_e32 v138, v146, v138
	v_add_f32_e32 v134, v135, v134
	v_add_f32_e32 v134, v138, v134
	v_lshlrev_b32_e32 v131, 2, v131
	v_add_f32_e32 v130, v134, v130
	v_bitop3_b32 v131, v131, 64, v220 bitop3:0x6c
	ds_bpermute_b32 v131, v131, v130
	s_waitcnt lgkmcnt(0)
	v_add_f32_e32 v130, v130, v131
	v_mov_b32_e32 v131, v179
	s_nop 0
	v_lshlrev_b32_e32 v131, 2, v131
	v_bitop3_b32 v131, v131, s33, v220 bitop3:0x6c
	ds_bpermute_b32 v131, v131, v130
	s_and_saveexec_b64 s[38:39], s[42:43]
	s_cbranch_execz .LBB0_98
	s_ashr_i32 s31, s30, 31
	s_lshl_b64 s[48:49], s[30:31], 18
	s_add_u32 s48, s20, s48
	s_addc_u32 s49, s46, s49
	s_waitcnt lgkmcnt(0)
	v_add_f32_e32 v132, v130, v131
	v_lshl_add_u64 v[130:131], v[186:187], 4, s[48:49]
	v_readlane_b32 s48, v237, 58
	v_readlane_b32 s49, v237, 59
	s_lshl_b32 s48, s64, 2
	s_mov_b32 s31, s49
	v_writelane_b32 v237, s30, 58
	v_lshl_add_u64 v[130:131], v[130:131], 0, s[48:49]
	global_store_dword v[130:131], v132, off sc1
	v_writelane_b32 v237, s31, 59

; __device__ __forceinline__ float shx(float v, int o) { const int idx = (((int)otid() & 63) ^ o) << 2; return __builtin_bit_cast(float, __builtin_amdgcn_ds_bpermute(idx, __builtin_bit_cast(int, v))); }
; __device__ __forceinline__ void epi_all_run(const void* Pk_, int l, int s, const f32x4 (&acc)[2][2][4][2], const pg8::Unit& u, int wr, int wc, int fr, int fq) {
;     ...
;             for (int g = 0; g < 8; ++g) {
;                 const int ai = g >> 2, m = g & 3, row = row0 + ai * 128 + m * 16;
;                 if (g < 7) { const int rown = row0 + ((g + 1) >> 2) * 128 + ((g + 1) & 3) * 16;
; #pragma unroll
;                     for (int bj = 0; bj < 2; ++bj)
; #pragma unroll
;                         for (int n = 0; n < 2; ++n) bb[(g + 1) & 1][bj][n] = *(const f32x4*)(base + (size_t)rown * DM + col0 + bj * 128 + n * 4); }
;                 float ss = 0.f;
; #pragma unroll
;                 for (int bj = 0; bj < 2; ++bj)
; #pragma unroll
;                     for (int n = 0; n < 2; ++n) {
;                         const f32x4 h = bb[g & 1][bj][n] + gv[bj][n] * acc[ai][bj][m][n];
;                         *(f32x4*)(out + (size_t)row * DM + col0 + bj * 128 + n * 4) = h;
;                         ss += (h[0] * h[0] + h[1] * h[1]) + (h[2] * h[2] + h[3] * h[3]);
;                     }
;                 if (nsite < 3 * DEPTH) {
;                     ss += shx(ss, 16); ss += shx(ss, 32);
;                     if (fq == 0) __hip_atomic_store(slots + ((size_t)u.pn * M + row) * 4 + wc, ss, __ATOMIC_RELAXED, __HIP_MEMORY_SCOPE_AGENT);
;                 }
;             }
.LBB0_99:
	v_or_b32_e32 v210, 48, v184
	v_ashrrev_i32_e32 v211, 31, v210
	v_lshlrev_b64 v[214:215], 12, v[210:211]
	v_lshl_add_u64 v[134:135], v[206:207], 0, v[214:215]
	global_load_dwordx4 v[158:161], v[134:135], off offset:16
	global_load_dwordx4 v[166:169], v[134:135], off
	s_waitcnt lgkmcnt(0)
	global_load_dwordx4 v[130:133], v[134:135], off offset:528
	global_load_dwordx4 v[146:149], v[134:135], off offset:512
	v_lshl_add_u64 v[212:213], v[200:201], 0, v[212:213]
	s_waitcnt vmcnt(10)
	v_pk_fma_f32 v[96:97], v[96:97], v[202:203], v[164:165]
	v_pk_fma_f32 v[94:95], v[94:95], v[204:205], v[162:163]
	v_pk_fma_f32 v[92:93], v[92:93], v[198:199], v[156:157]
	v_pk_fma_f32 v[90:91], v[90:91], v[196:197], v[154:155]
	s_waitcnt vmcnt(8)
	v_pk_fma_f32 v[88:89], v[88:89], v[192:193], v[152:153]
	v_pk_fma_f32 v[86:87], v[86:87], v[194:195], v[150:151]
	v_pk_fma_f32 v[84:85], v[84:85], v[190:191], v[144:145]
	v_pk_fma_f32 v[82:83], v[82:83], v[188:189], v[142:143]
	s_and_b64 vcc, exec, s[4:5]
	global_store_dwordx4 v[212:213], v[94:97], off
	global_store_dwordx4 v[212:213], v[90:93], off offset:16
	global_store_dwordx4 v[212:213], v[86:89], off offset:512
	global_store_dwordx4 v[212:213], v[82:85], off offset:528
	s_cbranch_vccnz .LBB0_103
	v_mul_f32_e32 v135, v95, v95
	v_fmac_f32_e32 v135, v94, v94
	v_mul_f32_e32 v134, v97, v97
	v_fmac_f32_e32 v134, v96, v96
	v_add_f32_e32 v134, v135, v134
	v_mul_f32_e32 v135, v91, v91
	v_mul_f32_e32 v136, v93, v93
	v_fmac_f32_e32 v135, v90, v90
	v_fmac_f32_e32 v136, v92, v92
	v_add_f32_e32 v135, v135, v136
	v_add_f32_e32 v134, v134, v135
	v_mul_f32_e32 v135, v87, v87
	v_mul_f32_e32 v136, v89, v89
	v_fmac_f32_e32 v135, v86, v86
	v_fmac_f32_e32 v136, v88, v88
	v_add_f32_e32 v135, v135, v136
	v_add_f32_e32 v134, v134, v135
	v_mul_f32_e32 v135, v83, v83
	v_mul_f32_e32 v136, v85, v85
	v_fmac_f32_e32 v135, v82, v82
	v_fmac_f32_e32 v136, v84, v84
	v_add_f32_e32 v135, v135, v136
	v_add_f32_e32 v134, v134, v135
	v_mov_b32_e32 v135, v179
	s_nop 0
	v_lshlrev_b32_e32 v135, 2, v135
	v_bitop3_b32 v135, v135, 64, v220 bitop3:0x6c
	ds_bpermute_b32 v135, v135, v134
	s_waitcnt lgkmcnt(0)
	v_add_f32_e32 v134, v134, v135
	v_mov_b32_e32 v135, v179
	s_nop 0
	v_lshlrev_b32_e32 v135, 2, v135
	v_bitop3_b32 v135, v135, s33, v220 bitop3:0x6c
	ds_bpermute_b32 v135, v135, v134
	s_and_saveexec_b64 s[38:39], s[42:43]
	s_cbranch_execz .LBB0_102
	s_ashr_i32 s31, s30, 31
	s_lshl_b64 s[48:49], s[30:31], 18
	s_add_u32 s48, s20, s48
	s_addc_u32 s49, s46, s49
	s_waitcnt lgkmcnt(0)
	v_add_f32_e32 v136, v134, v135
	v_lshl_add_u64 v[134:135], v[208:209], 4, s[48:49]
	v_readlane_b32 s48, v237, 58
	v_readlane_b32 s49, v237, 59
	s_lshl_b32 s48, s64, 2
	s_mov_b32 s31, s49
	v_writelane_b32 v237, s30, 58
	v_lshl_add_u64 v[134:135], v[134:135], 0, s[48:49]
	global_store_dword v[134:135], v136, off sc1
	v_writelane_b32 v237, s31, 59

; __device__ __forceinline__ float shx(float v, int o) { const int idx = (((int)otid() & 63) ^ o) << 2; return __builtin_bit_cast(float, __builtin_amdgcn_ds_bpermute(idx, __builtin_bit_cast(int, v))); }
; __device__ __forceinline__ void epi_all_run(const void* Pk_, int l, int s, const f32x4 (&acc)[2][2][4][2], const pg8::Unit& u, int wr, int wc, int fr, int fq) {
;     ...
;             for (int g = 0; g < 8; ++g) {
;                 const int ai = g >> 2, m = g & 3, row = row0 + ai * 128 + m * 16;
;                 if (g < 7) { const int rown = row0 + ((g + 1) >> 2) * 128 + ((g + 1) & 3) * 16;
; #pragma unroll
;                     for (int bj = 0; bj < 2; ++bj)
; #pragma unroll
;                         for (int n = 0; n < 2; ++n) bb[(g + 1) & 1][bj][n] = *(const f32x4*)(base + (size_t)rown * DM + col0 + bj * 128 + n * 4); }
;                 float ss = 0.f;
; #pragma unroll
;                 for (int bj = 0; bj < 2; ++bj)
; #pragma unroll
;                     for (int n = 0; n < 2; ++n) {
;                         const f32x4 h = bb[g & 1][bj][n] + gv[bj][n] * acc[ai][bj][m][n];
;                         *(f32x4*)(out + (size_t)row * DM + col0 + bj * 128 + n * 4) = h;
;                         ss += (h[0] * h[0] + h[1] * h[1]) + (h[2] * h[2] + h[3] * h[3]);
;                     }
;                 if (nsite < 3 * DEPTH) {
;                     ss += shx(ss, 16); ss += shx(ss, 32);
;                     if (fq == 0) __hip_atomic_store(slots + ((size_t)u.pn * M + row) * 4 + wc, ss, __ATOMIC_RELAXED, __HIP_MEMORY_SCOPE_AGENT);
;                 }
;             }
.LBB0_103:
	v_add_u32_e32 v208, 0x80, v184
	v_ashrrev_i32_e32 v209, 31, v208
	v_lshlrev_b64 v[212:213], 12, v[208:209]
	v_lshl_add_u64 v[138:139], v[206:207], 0, v[212:213]
	global_load_dwordx4 v[150:153], v[138:139], off offset:16
	global_load_dwordx4 v[162:165], v[138:139], off
	s_waitcnt lgkmcnt(0)
	global_load_dwordx4 v[134:137], v[138:139], off offset:528
	s_nop 0
	global_load_dwordx4 v[138:141], v[138:139], off offset:512
	v_lshl_add_u64 v[214:215], v[200:201], 0, v[214:215]
	s_waitcnt vmcnt(10)
	v_pk_fma_f32 v[80:81], v[80:81], v[202:203], v[168:169]
	v_pk_fma_f32 v[78:79], v[78:79], v[204:205], v[166:167]
	v_pk_fma_f32 v[76:77], v[76:77], v[198:199], v[160:161]
	v_pk_fma_f32 v[74:75], v[74:75], v[196:197], v[158:159]
	s_waitcnt vmcnt(8)
	v_pk_fma_f32 v[72:73], v[72:73], v[192:193], v[148:149]
	v_pk_fma_f32 v[70:71], v[70:71], v[194:195], v[146:147]
	v_pk_fma_f32 v[68:69], v[68:69], v[190:191], v[132:133]
	v_pk_fma_f32 v[66:67], v[66:67], v[188:189], v[130:131]
	s_and_b64 vcc, exec, s[4:5]
	global_store_dwordx4 v[214:215], v[78:81], off
	global_store_dwordx4 v[214:215], v[74:77], off offset:16
	global_store_dwordx4 v[214:215], v[70:73], off offset:512
	global_store_dwordx4 v[214:215], v[66:69], off offset:528
	s_cbranch_vccnz .LBB0_107
	v_mul_f32_e32 v143, v79, v79
	v_fmac_f32_e32 v143, v78, v78
	v_mul_f32_e32 v142, v81, v81
	v_fmac_f32_e32 v142, v80, v80
	v_add_f32_e32 v142, v143, v142
	v_mul_f32_e32 v143, v75, v75
	v_mul_f32_e32 v144, v77, v77
	v_fmac_f32_e32 v143, v74, v74
	v_fmac_f32_e32 v144, v76, v76
	v_mul_f32_e32 v131, v67, v67
	v_add_f32_e32 v143, v143, v144
	v_fmac_f32_e32 v131, v66, v66
	v_mul_f32_e32 v130, v69, v69
	v_add_f32_e32 v142, v142, v143
	v_mul_f32_e32 v143, v71, v71
	v_mul_f32_e32 v144, v73, v73
	v_fmac_f32_e32 v130, v68, v68
	v_fmac_f32_e32 v143, v70, v70
	v_fmac_f32_e32 v144, v72, v72
	v_add_f32_e32 v130, v131, v130
	v_mov_b32_e32 v131, v179
	v_add_f32_e32 v143, v143, v144
	v_add_f32_e32 v142, v142, v143
	v_lshlrev_b32_e32 v131, 2, v131
	v_add_f32_e32 v130, v142, v130
	v_bitop3_b32 v131, v131, 64, v220 bitop3:0x6c
	ds_bpermute_b32 v131, v131, v130
	s_waitcnt lgkmcnt(0)
	v_add_f32_e32 v130, v130, v131
	v_mov_b32_e32 v131, v179
	s_nop 0
	v_lshlrev_b32_e32 v131, 2, v131
	v_bitop3_b32 v131, v131, s33, v220 bitop3:0x6c
	ds_bpermute_b32 v131, v131, v130
	s_and_saveexec_b64 s[38:39], s[42:43]
	s_cbranch_execz .LBB0_106
	s_ashr_i32 s31, s30, 31
	s_lshl_b64 s[48:49], s[30:31], 18
	s_add_u32 s48, s20, s48
	s_addc_u32 s49, s46, s49
	s_waitcnt lgkmcnt(0)
	v_add_f32_e32 v132, v130, v131
	v_lshl_add_u64 v[130:131], v[210:211], 4, s[48:49]
	v_readlane_b32 s48, v237, 58
	v_readlane_b32 s49, v237, 59
	s_lshl_b32 s48, s64, 2
	s_mov_b32 s31, s49
	v_writelane_b32 v237, s30, 58
	v_lshl_add_u64 v[130:131], v[130:131], 0, s[48:49]
	global_store_dword v[130:131], v132, off sc1
	v_writelane_b32 v237, s31, 59

; __device__ __forceinline__ float shx(float v, int o) { const int idx = (((int)otid() & 63) ^ o) << 2; return __builtin_bit_cast(float, __builtin_amdgcn_ds_bpermute(idx, __builtin_bit_cast(int, v))); }
; __device__ __forceinline__ void epi_all_run(const void* Pk_, int l, int s, const f32x4 (&acc)[2][2][4][2], const pg8::Unit& u, int wr, int wc, int fr, int fq) {
;     ...
;             for (int g = 0; g < 8; ++g) {
;                 const int ai = g >> 2, m = g & 3, row = row0 + ai * 128 + m * 16;
;                 if (g < 7) { const int rown = row0 + ((g + 1) >> 2) * 128 + ((g + 1) & 3) * 16;
; #pragma unroll
;                     for (int bj = 0; bj < 2; ++bj)
; #pragma unroll
;                         for (int n = 0; n < 2; ++n) bb[(g + 1) & 1][bj][n] = *(const f32x4*)(base + (size_t)rown * DM + col0 + bj * 128 + n * 4); }
;                 float ss = 0.f;
; #pragma unroll
;                 for (int bj = 0; bj < 2; ++bj)
; #pragma unroll
;                     for (int n = 0; n < 2; ++n) {
;                         const f32x4 h = bb[g & 1][bj][n] + gv[bj][n] * acc[ai][bj][m][n];
;                         *(f32x4*)(out + (size_t)row * DM + col0 + bj * 128 + n * 4) = h;
;                         ss += (h[0] * h[0] + h[1] * h[1]) + (h[2] * h[2] + h[3] * h[3]);
;                     }
;                 if (nsite < 3 * DEPTH) {
;                     ss += shx(ss, 16); ss += shx(ss, 32);
;                     if (fq == 0) __hip_atomic_store(slots + ((size_t)u.pn * M + row) * 4 + wc, ss, __ATOMIC_RELAXED, __HIP_MEMORY_SCOPE_AGENT);
;                 }
;             }
.LBB0_107:
	v_or_b32_e32 v210, 16, v208
	v_ashrrev_i32_e32 v211, 31, v210
	v_lshlrev_b64 v[214:215], 12, v[210:211]
	v_lshl_add_u64 v[142:143], v[206:207], 0, v[214:215]
	global_load_dwordx4 v[154:157], v[142:143], off offset:16
	global_load_dwordx4 v[166:169], v[142:143], off
	s_waitcnt lgkmcnt(0)
	global_load_dwordx4 v[130:133], v[142:143], off offset:528
	s_nop 0
	global_load_dwordx4 v[142:145], v[142:143], off offset:512
	v_lshl_add_u64 v[158:159], v[200:201], 0, v[212:213]
	s_waitcnt vmcnt(10)
	v_pk_fma_f32 v[64:65], v[64:65], v[202:203], v[164:165]
	v_pk_fma_f32 v[62:63], v[62:63], v[204:205], v[162:163]
	v_pk_fma_f32 v[60:61], v[60:61], v[198:199], v[152:153]
	v_pk_fma_f32 v[58:59], v[58:59], v[196:197], v[150:151]
	s_waitcnt vmcnt(8)
	v_pk_fma_f32 v[56:57], v[56:57], v[192:193], v[140:141]
	v_pk_fma_f32 v[54:55], v[54:55], v[194:195], v[138:139]
	v_pk_fma_f32 v[52:53], v[52:53], v[190:191], v[136:137]
	v_pk_fma_f32 v[50:51], v[50:51], v[188:189], v[134:135]
	s_and_b64 vcc, exec, s[4:5]
	global_store_dwordx4 v[158:159], v[62:65], off
	global_store_dwordx4 v[158:159], v[58:61], off offset:16
	global_store_dwordx4 v[158:159], v[54:57], off offset:512
	global_store_dwordx4 v[158:159], v[50:53], off offset:528
	s_cbranch_vccnz .LBB0_111
	v_mul_f32_e32 v147, v63, v63
	v_fmac_f32_e32 v147, v62, v62
	v_mul_f32_e32 v146, v65, v65
	v_fmac_f32_e32 v146, v64, v64
	v_mul_f32_e32 v135, v51, v51
	v_add_f32_e32 v146, v147, v146
	v_mul_f32_e32 v147, v59, v59
	v_mul_f32_e32 v148, v61, v61
	v_mul_f32_e32 v139, v55, v55
	v_fmac_f32_e32 v135, v50, v50
	v_mul_f32_e32 v134, v53, v53
	v_fmac_f32_e32 v147, v58, v58
	v_fmac_f32_e32 v148, v60, v60
	v_fmac_f32_e32 v139, v54, v54
	v_mul_f32_e32 v138, v57, v57
	v_fmac_f32_e32 v134, v52, v52
	v_add_f32_e32 v147, v147, v148
	v_fmac_f32_e32 v138, v56, v56
	v_add_f32_e32 v134, v135, v134
	v_mov_b32_e32 v135, v179
	v_add_f32_e32 v146, v146, v147
	v_add_f32_e32 v138, v139, v138
	v_add_f32_e32 v138, v146, v138
	v_lshlrev_b32_e32 v135, 2, v135
	v_add_f32_e32 v134, v138, v134
	v_bitop3_b32 v135, v135, 64, v220 bitop3:0x6c
	ds_bpermute_b32 v135, v135, v134
	s_waitcnt lgkmcnt(0)
	v_add_f32_e32 v134, v134, v135
	v_mov_b32_e32 v135, v179
	s_nop 0
	v_lshlrev_b32_e32 v135, 2, v135
	v_bitop3_b32 v135, v135, s33, v220 bitop3:0x6c
	ds_bpermute_b32 v135, v135, v134
	s_and_saveexec_b64 s[38:39], s[42:43]
	s_cbranch_execz .LBB0_110
	s_ashr_i32 s31, s30, 31
	s_lshl_b64 s[48:49], s[30:31], 18
	s_add_u32 s48, s20, s48
	s_addc_u32 s49, s46, s49
	s_waitcnt lgkmcnt(0)
	v_add_f32_e32 v136, v134, v135
	v_lshl_add_u64 v[134:135], v[208:209], 4, s[48:49]
	v_readlane_b32 s48, v237, 58
	v_readlane_b32 s49, v237, 59
	s_lshl_b32 s48, s64, 2
	s_mov_b32 s31, s49
	v_writelane_b32 v237, s30, 58
	v_lshl_add_u64 v[134:135], v[134:135], 0, s[48:49]
	global_store_dword v[134:135], v136, off sc1
	v_writelane_b32 v237, s31, 59

; __device__ __forceinline__ float shx(float v, int o) { const int idx = (((int)otid() & 63) ^ o) << 2; return __builtin_bit_cast(float, __builtin_amdgcn_ds_bpermute(idx, __builtin_bit_cast(int, v))); }
; __device__ __forceinline__ void epi_all_run(const void* Pk_, int l, int s, const f32x4 (&acc)[2][2][4][2], const pg8::Unit& u, int wr, int wc, int fr, int fq) {
;     ...
;             for (int g = 0; g < 8; ++g) {
;                 const int ai = g >> 2, m = g & 3, row = row0 + ai * 128 + m * 16;
;                 if (g < 7) { const int rown = row0 + ((g + 1) >> 2) * 128 + ((g + 1) & 3) * 16;
; #pragma unroll
;                     for (int bj = 0; bj < 2; ++bj)
; #pragma unroll
;                         for (int n = 0; n < 2; ++n) bb[(g + 1) & 1][bj][n] = *(const f32x4*)(base + (size_t)rown * DM + col0 + bj * 128 + n * 4); }
;                 float ss = 0.f;
; #pragma unroll
;                 for (int bj = 0; bj < 2; ++bj)
; #pragma unroll
;                     for (int n = 0; n < 2; ++n) {
;                         const f32x4 h = bb[g & 1][bj][n] + gv[bj][n] * acc[ai][bj][m][n];
;                         *(f32x4*)(out + (size_t)row * DM + col0 + bj * 128 + n * 4) = h;
;                         ss += (h[0] * h[0] + h[1] * h[1]) + (h[2] * h[2] + h[3] * h[3]);
;                     }
;                 if (nsite < 3 * DEPTH) {
;                     ss += shx(ss, 16); ss += shx(ss, 32);
;                     if (fq == 0) __hip_atomic_store(slots + ((size_t)u.pn * M + row) * 4 + wc, ss, __ATOMIC_RELAXED, __HIP_MEMORY_SCOPE_AGENT);
;                 }
;             }
.LBB0_111:
	v_or_b32_e32 v162, 32, v208
	v_ashrrev_i32_e32 v163, 31, v162
	v_lshlrev_b64 v[212:213], 12, v[162:163]
	v_lshl_add_u64 v[138:139], v[206:207], 0, v[212:213]
	global_load_dwordx4 v[146:149], v[138:139], off offset:16
	global_load_dwordx4 v[158:161], v[138:139], off
	s_waitcnt lgkmcnt(0)
	global_load_dwordx4 v[134:137], v[138:139], off offset:528
	s_nop 0
	global_load_dwordx4 v[138:141], v[138:139], off offset:512
	v_lshl_add_u64 v[164:165], v[200:201], 0, v[214:215]
	s_waitcnt vmcnt(10)
	v_pk_fma_f32 v[48:49], v[48:49], v[202:203], v[168:169]
	v_pk_fma_f32 v[46:47], v[46:47], v[204:205], v[166:167]
	v_pk_fma_f32 v[44:45], v[44:45], v[198:199], v[156:157]
	v_pk_fma_f32 v[42:43], v[42:43], v[196:197], v[154:155]
	s_waitcnt vmcnt(8)
	v_pk_fma_f32 v[40:41], v[40:41], v[192:193], v[144:145]
	v_pk_fma_f32 v[38:39], v[38:39], v[194:195], v[142:143]
	v_pk_fma_f32 v[36:37], v[36:37], v[190:191], v[132:133]
	v_pk_fma_f32 v[34:35], v[34:35], v[188:189], v[130:131]
	s_and_b64 vcc, exec, s[4:5]
	global_store_dwordx4 v[164:165], v[46:49], off
	global_store_dwordx4 v[164:165], v[42:45], off offset:16
	global_store_dwordx4 v[164:165], v[38:41], off offset:512
	global_store_dwordx4 v[164:165], v[34:37], off offset:528
	s_cbranch_vccnz .LBB0_115
	v_mul_f32_e32 v151, v47, v47
	v_fmac_f32_e32 v151, v46, v46
	v_mul_f32_e32 v150, v49, v49
	v_fmac_f32_e32 v150, v48, v48
	v_mul_f32_e32 v131, v35, v35
	v_add_f32_e32 v150, v151, v150
	v_mul_f32_e32 v151, v43, v43
	v_mul_f32_e32 v152, v45, v45
	v_mul_f32_e32 v143, v39, v39
	v_fmac_f32_e32 v131, v34, v34
	v_mul_f32_e32 v130, v37, v37
	v_fmac_f32_e32 v151, v42, v42
	v_fmac_f32_e32 v152, v44, v44
	v_fmac_f32_e32 v143, v38, v38
	v_mul_f32_e32 v142, v41, v41
	v_fmac_f32_e32 v130, v36, v36
	v_add_f32_e32 v151, v151, v152
	v_fmac_f32_e32 v142, v40, v40
	v_add_f32_e32 v130, v131, v130
	v_mov_b32_e32 v131, v179
	v_add_f32_e32 v150, v150, v151
	v_add_f32_e32 v142, v143, v142
	v_add_f32_e32 v142, v150, v142
	v_lshlrev_b32_e32 v131, 2, v131
	v_add_f32_e32 v130, v142, v130
	v_bitop3_b32 v131, v131, 64, v220 bitop3:0x6c
	ds_bpermute_b32 v131, v131, v130
	s_waitcnt lgkmcnt(0)
	v_add_f32_e32 v130, v130, v131
	v_mov_b32_e32 v131, v179
	s_nop 0
	v_lshlrev_b32_e32 v131, 2, v131
	v_bitop3_b32 v131, v131, s33, v220 bitop3:0x6c
	ds_bpermute_b32 v131, v131, v130
	s_and_saveexec_b64 s[38:39], s[42:43]
	s_cbranch_execz .LBB0_114
	s_ashr_i32 s31, s30, 31
	s_lshl_b64 s[48:49], s[30:31], 18
	s_add_u32 s48, s20, s48
	s_addc_u32 s49, s46, s49
	s_waitcnt lgkmcnt(0)
	v_add_f32_e32 v132, v130, v131
	v_lshl_add_u64 v[130:131], v[210:211], 4, s[48:49]
	v_readlane_b32 s48, v237, 58
	v_readlane_b32 s49, v237, 59
	s_lshl_b32 s48, s64, 2
	s_mov_b32 s31, s49
	v_writelane_b32 v237, s30, 58
	v_lshl_add_u64 v[130:131], v[130:131], 0, s[48:49]
	global_store_dword v[130:131], v132, off sc1
	v_writelane_b32 v237, s31, 59

; __device__ __forceinline__ float shx(float v, int o) { const int idx = (((int)otid() & 63) ^ o) << 2; return __builtin_bit_cast(float, __builtin_amdgcn_ds_bpermute(idx, __builtin_bit_cast(int, v))); }
; __device__ __forceinline__ void epi_all_run(const void* Pk_, int l, int s, const f32x4 (&acc)[2][2][4][2], const pg8::Unit& u, int wr, int wc, int fr, int fq) {
;     ...
;             for (int g = 0; g < 8; ++g) {
;                 const int ai = g >> 2, m = g & 3, row = row0 + ai * 128 + m * 16;
;                 if (g < 7) { const int rown = row0 + ((g + 1) >> 2) * 128 + ((g + 1) & 3) * 16;
; #pragma unroll
;                     for (int bj = 0; bj < 2; ++bj)
; #pragma unroll
;                         for (int n = 0; n < 2; ++n) bb[(g + 1) & 1][bj][n] = *(const f32x4*)(base + (size_t)rown * DM + col0 + bj * 128 + n * 4); }
;                 float ss = 0.f;
; #pragma unroll
;                 for (int bj = 0; bj < 2; ++bj)
; #pragma unroll
;                     for (int n = 0; n < 2; ++n) {
;                         const f32x4 h = bb[g & 1][bj][n] + gv[bj][n] * acc[ai][bj][m][n];
;                         *(f32x4*)(out + (size_t)row * DM + col0 + bj * 128 + n * 4) = h;
;                         ss += (h[0] * h[0] + h[1] * h[1]) + (h[2] * h[2] + h[3] * h[3]);
;                     }
;                 if (nsite < 3 * DEPTH) {
;                     ss += shx(ss, 16); ss += shx(ss, 32);
;                     if (fq == 0) __hip_atomic_store(slots + ((size_t)u.pn * M + row) * 4 + wc, ss, __ATOMIC_RELAXED, __HIP_MEMORY_SCOPE_AGENT);
;                 }
;             }
.LBB0_115:
	v_or_b32_e32 v164, 48, v208
	v_ashrrev_i32_e32 v165, 31, v164
	v_lshlrev_b64 v[166:167], 12, v[164:165]
	v_lshl_add_u64 v[142:143], v[206:207], 0, v[166:167]
	global_load_dwordx4 v[150:153], v[142:143], off offset:16
	global_load_dwordx4 v[154:157], v[142:143], off
	s_waitcnt lgkmcnt(0)
	global_load_dwordx4 v[130:133], v[142:143], off offset:528
	s_nop 0
	global_load_dwordx4 v[142:145], v[142:143], off offset:512
	v_lshl_add_u64 v[168:169], v[200:201], 0, v[212:213]
	s_waitcnt vmcnt(10)
	v_pk_fma_f32 v[32:33], v[32:33], v[202:203], v[160:161]
	v_pk_fma_f32 v[30:31], v[30:31], v[204:205], v[158:159]
	v_pk_fma_f32 v[28:29], v[28:29], v[198:199], v[148:149]
	v_pk_fma_f32 v[26:27], v[26:27], v[196:197], v[146:147]
	s_waitcnt vmcnt(8)
	v_pk_fma_f32 v[24:25], v[24:25], v[192:193], v[140:141]
	v_pk_fma_f32 v[22:23], v[22:23], v[194:195], v[138:139]
	v_pk_fma_f32 v[20:21], v[20:21], v[190:191], v[136:137]
	v_pk_fma_f32 v[18:19], v[18:19], v[188:189], v[134:135]
	s_and_b64 vcc, exec, s[4:5]
	global_store_dwordx4 v[168:169], v[30:33], off
	global_store_dwordx4 v[168:169], v[26:29], off offset:16
	global_store_dwordx4 v[168:169], v[22:25], off offset:512
	global_store_dwordx4 v[168:169], v[18:21], off offset:528
	s_cbranch_vccnz .LBB0_119
	v_mul_f32_e32 v159, v31, v31
	v_mul_f32_e32 v147, v27, v27
	v_mul_f32_e32 v135, v19, v19
	v_fmac_f32_e32 v159, v30, v30
	v_mul_f32_e32 v158, v33, v33
	v_fmac_f32_e32 v147, v26, v26
	v_mul_f32_e32 v146, v29, v29
	v_mul_f32_e32 v139, v23, v23
	v_fmac_f32_e32 v135, v18, v18
	v_mul_f32_e32 v134, v21, v21
	v_fmac_f32_e32 v158, v32, v32
	v_fmac_f32_e32 v146, v28, v28
	v_fmac_f32_e32 v139, v22, v22
	v_mul_f32_e32 v138, v25, v25
	v_fmac_f32_e32 v134, v20, v20
	v_add_f32_e32 v158, v159, v158
	v_add_f32_e32 v146, v147, v146
	v_fmac_f32_e32 v138, v24, v24
	v_add_f32_e32 v134, v135, v134
	v_mov_b32_e32 v135, v179
	v_add_f32_e32 v146, v158, v146
	v_add_f32_e32 v138, v139, v138
	v_add_f32_e32 v138, v146, v138
	v_lshlrev_b32_e32 v135, 2, v135
	v_add_f32_e32 v134, v138, v134
	v_bitop3_b32 v135, v135, 64, v220 bitop3:0x6c
	ds_bpermute_b32 v135, v135, v134
	s_waitcnt lgkmcnt(0)
	v_add_f32_e32 v134, v134, v135
	v_mov_b32_e32 v135, v179
	s_nop 0
	v_lshlrev_b32_e32 v135, 2, v135
	v_bitop3_b32 v135, v135, s33, v220 bitop3:0x6c
	ds_bpermute_b32 v135, v135, v134
	s_and_saveexec_b64 s[38:39], s[42:43]
	s_cbranch_execz .LBB0_118
	s_ashr_i32 s31, s30, 31
	s_lshl_b64 s[48:49], s[30:31], 18
	s_add_u32 s48, s20, s48
	s_addc_u32 s49, s46, s49
	s_waitcnt lgkmcnt(0)
	v_add_f32_e32 v136, v134, v135
	v_lshl_add_u64 v[134:135], v[162:163], 4, s[48:49]
	v_readlane_b32 s48, v237, 58
	v_readlane_b32 s49, v237, 59
	s_lshl_b32 s48, s64, 2
	s_mov_b32 s31, s49
	v_writelane_b32 v237, s30, 58
	v_lshl_add_u64 v[134:135], v[134:135], 0, s[48:49]
	global_store_dword v[134:135], v136, off sc1
	v_writelane_b32 v237, s31, 59

; __device__ __forceinline__ float shx(float v, int o) { const int idx = (((int)otid() & 63) ^ o) << 2; return __builtin_bit_cast(float, __builtin_amdgcn_ds_bpermute(idx, __builtin_bit_cast(int, v))); }
; __device__ __forceinline__ void epi_all_run(const void* Pk_, int l, int s, const f32x4 (&acc)[2][2][4][2], const pg8::Unit& u, int wr, int wc, int fr, int fq) {
;     ...
;             for (int g = 0; g < 8; ++g) {
;                 const int ai = g >> 2, m = g & 3, row = row0 + ai * 128 + m * 16;
;                 if (g < 7) { const int rown = row0 + ((g + 1) >> 2) * 128 + ((g + 1) & 3) * 16;
; #pragma unroll
;                     for (int bj = 0; bj < 2; ++bj)
; #pragma unroll
;                         for (int n = 0; n < 2; ++n) bb[(g + 1) & 1][bj][n] = *(const f32x4*)(base + (size_t)rown * DM + col0 + bj * 128 + n * 4); }
;                 float ss = 0.f;
; #pragma unroll
;                 for (int bj = 0; bj < 2; ++bj)
; #pragma unroll
;                     for (int n = 0; n < 2; ++n) {
;                         const f32x4 h = bb[g & 1][bj][n] + gv[bj][n] * acc[ai][bj][m][n];
;                         *(f32x4*)(out + (size_t)row * DM + col0 + bj * 128 + n * 4) = h;
;                         ss += (h[0] * h[0] + h[1] * h[1]) + (h[2] * h[2] + h[3] * h[3]);
;                     }
;                 if (nsite < 3 * DEPTH) {
;                     ss += shx(ss, 16); ss += shx(ss, 32);
;                     if (fq == 0) __hip_atomic_store(slots + ((size_t)u.pn * M + row) * 4 + wc, ss, __ATOMIC_RELAXED, __HIP_MEMORY_SCOPE_AGENT);
;                 }
;             }
.LBB0_119:
	v_lshl_add_u64 v[146:147], v[200:201], 0, v[166:167]
	s_waitcnt vmcnt(6)
	v_pk_fma_f32 v[16:17], v[16:17], v[202:203], v[156:157]
	s_waitcnt lgkmcnt(0)
	v_pk_fma_f32 v[14:15], v[14:15], v[204:205], v[154:155]
	v_pk_fma_f32 v[12:13], v[12:13], v[198:199], v[152:153]
	v_pk_fma_f32 v[10:11], v[10:11], v[196:197], v[150:151]
	s_waitcnt vmcnt(4)
	v_pk_fma_f32 v[8:9], v[8:9], v[192:193], v[144:145]
	v_pk_fma_f32 v[6:7], v[6:7], v[194:195], v[142:143]
	v_pk_fma_f32 v[4:5], v[4:5], v[190:191], v[132:133]
	v_pk_fma_f32 v[2:3], v[2:3], v[188:189], v[130:131]
	s_and_b64 vcc, exec, s[4:5]
	global_store_dwordx4 v[146:147], v[14:17], off
	global_store_dwordx4 v[146:147], v[10:13], off offset:16
	global_store_dwordx4 v[146:147], v[6:9], off offset:512
	global_store_dwordx4 v[146:147], v[2:5], off offset:528
	s_cbranch_vccnz .LBB0_123
	v_mul_f32_e32 v135, v15, v15
	v_fmac_f32_e32 v135, v14, v14
	v_mul_f32_e32 v134, v17, v17
	v_fmac_f32_e32 v134, v16, v16
	v_add_f32_e32 v134, v135, v134
	v_mul_f32_e32 v135, v11, v11
	v_mul_f32_e32 v136, v13, v13
	v_fmac_f32_e32 v135, v10, v10
	v_fmac_f32_e32 v136, v12, v12
	v_mul_f32_e32 v131, v3, v3
	v_add_f32_e32 v135, v135, v136
	v_fmac_f32_e32 v131, v2, v2
	v_mul_f32_e32 v130, v5, v5
	v_add_f32_e32 v134, v134, v135
	v_mul_f32_e32 v135, v7, v7
	v_mul_f32_e32 v136, v9, v9
	v_fmac_f32_e32 v130, v4, v4
	v_fmac_f32_e32 v135, v6, v6
	v_fmac_f32_e32 v136, v8, v8
	v_add_f32_e32 v130, v131, v130
	v_mov_b32_e32 v131, v179
	v_add_f32_e32 v135, v135, v136
	v_add_f32_e32 v134, v134, v135
	v_lshlrev_b32_e32 v131, 2, v131
	v_add_f32_e32 v130, v134, v130
	v_bitop3_b32 v131, v131, 64, v220 bitop3:0x6c
	ds_bpermute_b32 v131, v131, v130
	s_waitcnt lgkmcnt(0)
	v_add_f32_e32 v130, v130, v131
	v_mov_b32_e32 v131, v179
	s_nop 0
	v_lshlrev_b32_e32 v131, 2, v131
	v_bitop3_b32 v131, v131, s33, v220 bitop3:0x6c
	ds_bpermute_b32 v131, v131, v130
	s_and_saveexec_b64 s[4:5], s[42:43]
	s_cbranch_execz .LBB0_122
	s_ashr_i32 s31, s30, 31
	s_lshl_b64 s[38:39], s[30:31], 18
	s_add_u32 s38, s20, s38
	s_addc_u32 s39, s46, s39
	s_waitcnt lgkmcnt(0)
	v_add_f32_e32 v132, v130, v131
	v_lshl_add_u64 v[130:131], v[164:165], 4, s[38:39]
	v_readlane_b32 s38, v237, 58
	v_readlane_b32 s39, v237, 59
	s_lshl_b32 s38, s64, 2
	s_mov_b32 s31, s39
	v_writelane_b32 v237, s30, 58
	v_lshl_add_u64 v[130:131], v[130:131], 0, s[38:39]
	global_store_dword v[130:131], v132, off sc1
	v_writelane_b32 v237, s31, 59

; __device__ __forceinline__ void fused_norm_tail(CA& A, int l, int s) {
;     const int nsite = 3 * l + (s == 1 ? 1 : (s == 4 ? 2 : 3));
;     if (nsite >= 3 * DEPTH) return;
;     const int tid = otid(), lane = tid & 63, wave = __builtin_amdgcn_readfirstlane(tid >> 6);
;     pg8::StaticOrder S; S.init(M, DM, (int)gridDim.x, (int)blockIdx.x); pg8::Unit u;
;     if (!S.next(0, u)) return;
;     unsigned char* const ws = A.ws;
;     const int nl = nsite / 3, nw = nsite % 3, b = u.pm >> 4;
;     const float* slots = (const float*)(ws + WS_RSP) + (size_t)nsite * M * 16;
;     unsigned* cnt = (unsigned*)(ws + WS_PCNT) + ((size_t)nsite * 64 + u.pm) * 16;
;     asm volatile("s_waitcnt vmcnt(0)" ::: "memory");
;     __syncthreads();
;     const float* MODn = (const float*)(ws + WS_MOD) + (size_t)(nl * 4 + b) * NMODC + (3 * nw) * DM;
;     const int col = u.pn * 256 + 4 * lane;
;     const float* hbase = A.out; bf16_t* xn = (bf16_t*)(ws + WS_XN);
;     f32x4 hrow[32];
; #pragma unroll
;     for (int r = 0; r < 32; ++r) hrow[r] = *(const f32x4*)(hbase + (size_t)(u.pm * 256 + wave * 32 + r) * DM + col);
;     const f32x4 ca = *(const f32x4*)(A.norm_g + (size_t)nsite * DM + col) * (1.0f + *(const f32x4*)(MODn + DM + col)), cb = *(const f32x4*)(MODn + col);
;     if (tid == 0) {
;         __hip_atomic_fetch_add(cnt, 1u, __ATOMIC_RELAXED, __HIP_MEMORY_SCOPE_AGENT);
;         unsigned spins = 0;
;         while (__hip_atomic_load(cnt, __ATOMIC_RELAXED, __HIP_MEMORY_SCOPE_AGENT) < 4u) { __builtin_amdgcn_s_sleep(2); if (++spins > (1u << 22)) break; }
;     }
;     __syncthreads();
;     float rstd_l = 0.f;
;     {
;         const int row = u.pm * 256 + wave * 32 + (lane & 31);
;         float ss = 0.f;
; #pragma unroll
;         for (int t = 0; t < 4; ++t) {
;             const unsigned long long* sp = (const unsigned long long*)(slots + ((size_t)t * M + row) * 4);
;             const unsigned long long w0 = __hip_atomic_load(sp, __ATOMIC_RELAXED, __HIP_MEMORY_SCOPE_AGENT), w1 = __hip_atomic_load(sp + 1, __ATOMIC_RELAXED, __HIP_MEMORY_SCOPE_AGENT);
;             ss += (__uint_as_float((unsigned)w0) + __uint_as_float((unsigned)(w0 >> 32))) + (__uint_as_float((unsigned)w1) + __uint_as_float((unsigned)(w1 >> 32)));
;         }
;         rstd_l = rsqrtf(ss * (1.0f / DM) + EPS);
;     }
.Lmy_tail:
	v_readlane_b32 s4, v237, 63
	v_readlane_b32 s5, v236, 0
	v_readlane_b32 s12, v237, 62
	v_readfirstlane_b32 s18, v179
	s_load_dwordx2 s[8:9], s[4:5], 0xc8
	s_load_dwordx2 s[10:11], s[4:5], 0x20
	s_and_b32 s13, s12, 7
	s_lshl_b32 s13, s13, 3
	s_bfe_u32 s14, s12, 0x30003
	s_add_i32 s13, s13, s14
	s_lshr_b32 s14, s12, 6
	s_mul_i32 s15, s80, 0x5556
	s_lshr_b32 s15, s15, 16
	s_mul_i32 s16, s15, 3
	s_sub_i32 s16, s80, s16
	s_lshr_b32 s17, s13, 4
	s_lshr_b32 s18, s18, 6
	s_lshr_b32 s19, s18, 2
	s_and_b32 s20, s18, 3
	v_and_b32_e32 v212, 63, v179
	v_and_b32_e32 v213, 15, v212
	v_lshrrev_b32_e32 v214, 4, v212
	s_lshl_b32 s24, s14, 8
	s_lshl_b32 s25, s20, 5
	s_add_i32 s24, s24, s25
	v_lshl_add_u32 v215, v214, 3, s24
	v_lshlrev_b32_e32 v211, 2, v215
	s_waitcnt lgkmcnt(0)
	s_lshl_b32 s25, s80, 12
	s_add_u32 s26, s10, s25
	s_addc_u32 s27, s11, 0
	s_lshl_b32 s25, s15, 2
	s_add_i32 s25, s25, s17
	s_mul_i32 s25, s25, 0x9000
	s_mul_i32 s28, s16, 0x3000
	s_add_i32 s25, s25, s28
	s_add_i32 s25, s25, 0x10000
	s_add_u32 s28, s8, s25
	s_addc_u32 s29, s9, 0
	s_add_u32 s30, s28, 0x1000
	s_addc_u32 s31, s29, 0
	s_lshl_b32 s25, s80, 6
	s_add_i32 s25, s25, s13
	s_lshl_b32 s25, s25, 6
	s_add_i32 s25, s25, 0x8000
	s_add_u32 s46, s8, s25
	s_addc_u32 s47, s9, 0
	s_lshl_b32 s25, s80, 20
	s_add_u32 s42, s8, s25
	s_addc_u32 s43, s9, 0
	s_add_u32 s42, s42, 0xed00000
	s_addc_u32 s43, s43, 0
	s_lshl_b32 s25, s13, 8
	s_lshl_b32 s48, s19, 6
	s_add_i32 s25, s25, s48
	s_lshl_b32 s48, s25, 11
	s_add_u32 s38, s8, s48
	s_addc_u32 s39, s9, 0
	s_add_u32 s38, s38, 0x5500000
	s_addc_u32 s39, s39, 0
	s_waitcnt vmcnt(0)
	s_barrier
	global_load_dwordx4 v[130:133], v211, s[26:27]
	global_load_dwordx4 v[146:149], v211, s[30:31]
	global_load_dwordx4 v[162:165], v211, s[28:29]
	global_load_dwordx4 v[134:137], v211, s[26:27] offset:16
	global_load_dwordx4 v[150:153], v211, s[30:31] offset:16
	global_load_dwordx4 v[166:169], v211, s[28:29] offset:16
	global_load_dwordx4 v[138:141], v211, s[26:27] offset:512
	global_load_dwordx4 v[154:157], v211, s[30:31] offset:512
	global_load_dwordx4 v[170:173], v211, s[28:29] offset:512
	global_load_dwordx4 v[142:145], v211, s[26:27] offset:528
	global_load_dwordx4 v[158:161], v211, s[30:31] offset:528
	global_load_dwordx4 v[174:177], v211, s[28:29] offset:528
	s_mov_b64 s[4:5], exec
	v_readlane_b32 s6, v238, 8
	v_readlane_b32 s7, v238, 9
	s_nop 1
	s_and_b64 s[6:7], s[4:5], s[6:7]
	s_mov_b64 exec, s[6:7]
	s_cbranch_execz .Lmy_tail_arrived
	v_mov_b32_e32 v1, 1
	s_mov_b32 s48, 0
	global_atomic_add v0, v1, s[46:47]
.Lmy_tail_spin:
	global_load_dword v1, v0, s[46:47] sc1
	s_add_i32 s48, s48, 1
	s_waitcnt vmcnt(0)
	v_cmp_lt_u32_e32 vcc, 3, v1
	s_cbranch_vccnz .Lmy_tail_arrived
	s_cmp_lt_u32 s48, 0x400000
	s_cbranch_scc0 .Lmy_tail_arrived
	s_sleep 2
	s_branch .Lmy_tail_spin
.Lmy_tail_arrived:
	s_mov_b64 exec, s[4:5]
	s_waitcnt vmcnt(0)
	v_pk_add_f32 v[146:147], v[146:147], 1.0 op_sel_hi:[1,0]
	v_pk_add_f32 v[148:149], v[148:149], 1.0 op_sel_hi:[1,0]
	v_pk_add_f32 v[150:151], v[150:151], 1.0 op_sel_hi:[1,0]
	v_pk_add_f32 v[152:153], v[152:153], 1.0 op_sel_hi:[1,0]
	v_pk_add_f32 v[154:155], v[154:155], 1.0 op_sel_hi:[1,0]
	v_pk_add_f32 v[156:157], v[156:157], 1.0 op_sel_hi:[1,0]
	v_pk_add_f32 v[158:159], v[158:159], 1.0 op_sel_hi:[1,0]
	v_pk_add_f32 v[160:161], v[160:161], 1.0 op_sel_hi:[1,0]
	v_pk_mul_f32 v[130:131], v[130:131], v[146:147]
	v_pk_mul_f32 v[132:133], v[132:133], v[148:149]
	v_pk_mul_f32 v[134:135], v[134:135], v[150:151]
	v_pk_mul_f32 v[136:137], v[136:137], v[152:153]
	v_pk_mul_f32 v[138:139], v[138:139], v[154:155]
	v_pk_mul_f32 v[140:141], v[140:141], v[156:157]
	v_pk_mul_f32 v[142:143], v[142:143], v[158:159]
	v_pk_mul_f32 v[144:145], v[144:145], v[160:161]
	s_barrier
	v_lshl_add_u32 v210, v212, 4, 0
	s_lshl_b32 s48, s25, 4
	v_add_u32_e32 v210, s48, v210
	s_mov_b32 s44, s42
	s_mov_b32 s45, s43
	global_load_dwordx4 v[146:149], v210, s[44:45] sc1
	global_load_dwordx4 v[196:199], v210, s[44:45] offset:2048 sc1
	s_add_u32 s44, s44, 0x40000
	s_addc_u32 s45, s45, 0
	global_load_dwordx4 v[150:153], v210, s[44:45] sc1
	global_load_dwordx4 v[200:203], v210, s[44:45] offset:2048 sc1
	s_add_u32 s44, s44, 0x40000
	s_addc_u32 s45, s45, 0
	global_load_dwordx4 v[154:157], v210, s[44:45] sc1
	global_load_dwordx4 v[204:207], v210, s[44:45] offset:2048 sc1
	s_add_u32 s44, s44, 0x40000
	s_addc_u32 s45, s45, 0
	global_load_dwordx4 v[158:161], v210, s[44:45] sc1
	global_load_dwordx4 v[192:195], v210, s[44:45] offset:2048 sc1
	s_waitcnt vmcnt(0)
	v_add_f32_e32 v208, v146, v147
	v_add_f32_e32 v210, v148, v149
	v_add_f32_e32 v208, v208, v210
	v_add_f32_e32 v208, 0, v208
	v_add_f32_e32 v211, v150, v151
	v_add_f32_e32 v210, v152, v153
	v_add_f32_e32 v210, v211, v210
	v_add_f32_e32 v208, v208, v210
	v_add_f32_e32 v211, v154, v155
	v_add_f32_e32 v210, v156, v157
	v_add_f32_e32 v210, v211, v210
	v_add_f32_e32 v208, v208, v210
	v_add_f32_e32 v211, v158, v159
	v_add_f32_e32 v210, v160, v161
	v_add_f32_e32 v210, v211, v210
	v_add_f32_e32 v208, v208, v210
	v_fmamk_f32 v208, v208, 0x3a800000, v216
	v_cmp_gt_f32_e32 vcc, s0, v208
	v_mul_f32_e32 v210, 0x4b800000, v208
	s_nop 0
	v_cndmask_b32_e32 v208, v208, v210, vcc
	v_rsq_f32_e32 v208, v208
	s_nop 0
	v_mul_f32_e32 v210, 0x45800000, v208
	v_cndmask_b32_e32 v208, v208, v210, vcc
	v_add_f32_e32 v209, v196, v197
	v_add_f32_e32 v210, v198, v199
	v_add_f32_e32 v209, v209, v210
	v_add_f32_e32 v209, 0, v209
	v_add_f32_e32 v211, v200, v201
	v_add_f32_e32 v210, v202, v203
	v_add_f32_e32 v210, v211, v210
	v_add_f32_e32 v209, v209, v210
	v_add_f32_e32 v211, v204, v205
	v_add_f32_e32 v210, v206, v207
	v_add_f32_e32 v210, v211, v210
	v_add_f32_e32 v209, v209, v210
	v_add_f32_e32 v211, v192, v193
	v_add_f32_e32 v210, v194, v195
	v_add_f32_e32 v210, v211, v210
	v_add_f32_e32 v209, v209, v210
	v_fmamk_f32 v209, v209, 0x3a800000, v216
	v_cmp_gt_f32_e32 vcc, s0, v209
	v_mul_f32_e32 v210, 0x4b800000, v209
	s_nop 0
	v_cndmask_b32_e32 v209, v209, v210, vcc
	v_rsq_f32_e32 v209, v209
	s_nop 0
	v_mul_f32_e32 v210, 0x45800000, v209
	v_cndmask_b32_e32 v209, v209, v210, vcc
	v_lshlrev_b32_e32 v206, 2, v213
	v_add_u32_e32 v201, 64, v206
	v_add_u32_e32 v202, 128, v206
	v_add_u32_e32 v203, 192, v206
	ds_bpermute_b32 v180, v206, v208
	ds_bpermute_b32 v188, v206, v209
	ds_bpermute_b32 v182, v201, v208
	ds_bpermute_b32 v190, v201, v209
	ds_bpermute_b32 v184, v202, v208
	ds_bpermute_b32 v192, v202, v209
	ds_bpermute_b32 v186, v203, v208
	ds_bpermute_b32 v194, v203, v209
	v_lshlrev_b32_e32 v204, 11, v213
	v_lshl_add_u32 v204, v215, 1, v204
	s_waitcnt lgkmcnt(0)
; __device__ __forceinline__ unsigned pk2(float lo, float hi) { f32x2_t v = {lo, hi}; bf16x2_t b = __builtin_convertvector(v, bf16x2_t); return __builtin_bit_cast(unsigned, b); }
; __device__ __forceinline__ void fused_norm_tail(CA& A, int l, int s) {
;     ...
; #pragma unroll
;     for (int r = 0; r < 32; ++r) {
;         const int row = u.pm * 256 + wave * 32 + r;
;         const float rstd = __builtin_bit_cast(float, __builtin_amdgcn_readlane(__builtin_bit_cast(int, rstd_l), r));
;         const f32x4 y = hrow[r] * rstd * ca + cb;
;         v2u o; o.x = pk2(y.x, y.y); o.y = pk2(y.z, y.w);
;         *(v2u*)(xn + (size_t)row * DM + col) = o;
;     }
	s_add_u32 s40, s38, 0x0
	s_addc_u32 s41, s39, 0
	v_pk_mul_f32 v[126:127], v[126:127], v[180:181] op_sel_hi:[1,0]
	v_pk_mul_f32 v[128:129], v[128:129], v[180:181] op_sel_hi:[1,0]
	v_pk_mul_f32 v[122:123], v[122:123], v[180:181] op_sel_hi:[1,0]
	v_pk_mul_f32 v[124:125], v[124:125], v[180:181] op_sel_hi:[1,0]
	v_pk_fma_f32 v[126:127], v[130:131], v[126:127], v[162:163]
	v_pk_fma_f32 v[128:129], v[132:133], v[128:129], v[164:165]
	v_pk_fma_f32 v[122:123], v[134:135], v[122:123], v[166:167]
	v_pk_fma_f32 v[124:125], v[136:137], v[124:125], v[168:169]
	v_cvt_pk_bf16_f32 v126, v126, v127
	v_cvt_pk_bf16_f32 v127, v128, v129
	v_cvt_pk_bf16_f32 v128, v122, v123
	v_cvt_pk_bf16_f32 v129, v124, v125
	global_store_dwordx4 v204, v[126:129], s[40:41]
	v_pk_mul_f32 v[118:119], v[118:119], v[180:181] op_sel_hi:[1,0]
	v_pk_mul_f32 v[120:121], v[120:121], v[180:181] op_sel_hi:[1,0]
	v_pk_mul_f32 v[114:115], v[114:115], v[180:181] op_sel_hi:[1,0]
	v_pk_mul_f32 v[116:117], v[116:117], v[180:181] op_sel_hi:[1,0]
	v_pk_fma_f32 v[118:119], v[138:139], v[118:119], v[170:171]
	v_pk_fma_f32 v[120:121], v[140:141], v[120:121], v[172:173]
	v_pk_fma_f32 v[114:115], v[142:143], v[114:115], v[174:175]
	v_pk_fma_f32 v[116:117], v[144:145], v[116:117], v[176:177]
	v_cvt_pk_bf16_f32 v118, v118, v119
	v_cvt_pk_bf16_f32 v119, v120, v121
	v_cvt_pk_bf16_f32 v120, v114, v115
	v_cvt_pk_bf16_f32 v121, v116, v117
	global_store_dwordx4 v204, v[118:121], s[40:41] offset:256
	s_add_u32 s40, s38, 0x8000
	s_addc_u32 s41, s39, 0
	v_pk_mul_f32 v[110:111], v[110:111], v[182:183] op_sel_hi:[1,0]
	v_pk_mul_f32 v[112:113], v[112:113], v[182:183] op_sel_hi:[1,0]
	v_pk_mul_f32 v[106:107], v[106:107], v[182:183] op_sel_hi:[1,0]
	v_pk_mul_f32 v[108:109], v[108:109], v[182:183] op_sel_hi:[1,0]
	v_pk_fma_f32 v[110:111], v[130:131], v[110:111], v[162:163]
	v_pk_fma_f32 v[112:113], v[132:133], v[112:113], v[164:165]
	v_pk_fma_f32 v[106:107], v[134:135], v[106:107], v[166:167]
	v_pk_fma_f32 v[108:109], v[136:137], v[108:109], v[168:169]
	v_cvt_pk_bf16_f32 v110, v110, v111
	v_cvt_pk_bf16_f32 v111, v112, v113
	v_cvt_pk_bf16_f32 v112, v106, v107
	v_cvt_pk_bf16_f32 v113, v108, v109
	global_store_dwordx4 v204, v[110:113], s[40:41]
	v_pk_mul_f32 v[102:103], v[102:103], v[182:183] op_sel_hi:[1,0]
	v_pk_mul_f32 v[104:105], v[104:105], v[182:183] op_sel_hi:[1,0]
	v_pk_mul_f32 v[98:99], v[98:99], v[182:183] op_sel_hi:[1,0]
	v_pk_mul_f32 v[100:101], v[100:101], v[182:183] op_sel_hi:[1,0]
	v_pk_fma_f32 v[102:103], v[138:139], v[102:103], v[170:171]
	v_pk_fma_f32 v[104:105], v[140:141], v[104:105], v[172:173]
	v_pk_fma_f32 v[98:99], v[142:143], v[98:99], v[174:175]
	v_pk_fma_f32 v[100:101], v[144:145], v[100:101], v[176:177]
	v_cvt_pk_bf16_f32 v102, v102, v103
	v_cvt_pk_bf16_f32 v103, v104, v105
	v_cvt_pk_bf16_f32 v104, v98, v99
	v_cvt_pk_bf16_f32 v105, v100, v101
	global_store_dwordx4 v204, v[102:105], s[40:41] offset:256
	s_add_u32 s40, s38, 0x10000
	s_addc_u32 s41, s39, 0
	v_pk_mul_f32 v[94:95], v[94:95], v[184:185] op_sel_hi:[1,0]
	v_pk_mul_f32 v[96:97], v[96:97], v[184:185] op_sel_hi:[1,0]
	v_pk_mul_f32 v[90:91], v[90:91], v[184:185] op_sel_hi:[1,0]
	v_pk_mul_f32 v[92:93], v[92:93], v[184:185] op_sel_hi:[1,0]
	v_pk_fma_f32 v[94:95], v[130:131], v[94:95], v[162:163]
	v_pk_fma_f32 v[96:97], v[132:133], v[96:97], v[164:165]
	v_pk_fma_f32 v[90:91], v[134:135], v[90:91], v[166:167]
	v_pk_fma_f32 v[92:93], v[136:137], v[92:93], v[168:169]
	v_cvt_pk_bf16_f32 v94, v94, v95
	v_cvt_pk_bf16_f32 v95, v96, v97
	v_cvt_pk_bf16_f32 v96, v90, v91
	v_cvt_pk_bf16_f32 v97, v92, v93
	global_store_dwordx4 v204, v[94:97], s[40:41]
	v_pk_mul_f32 v[86:87], v[86:87], v[184:185] op_sel_hi:[1,0]
	v_pk_mul_f32 v[88:89], v[88:89], v[184:185] op_sel_hi:[1,0]
	v_pk_mul_f32 v[82:83], v[82:83], v[184:185] op_sel_hi:[1,0]
	v_pk_mul_f32 v[84:85], v[84:85], v[184:185] op_sel_hi:[1,0]
	v_pk_fma_f32 v[86:87], v[138:139], v[86:87], v[170:171]
	v_pk_fma_f32 v[88:89], v[140:141], v[88:89], v[172:173]
	v_pk_fma_f32 v[82:83], v[142:143], v[82:83], v[174:175]
	v_pk_fma_f32 v[84:85], v[144:145], v[84:85], v[176:177]
	v_cvt_pk_bf16_f32 v86, v86, v87
	v_cvt_pk_bf16_f32 v87, v88, v89
	v_cvt_pk_bf16_f32 v88, v82, v83
	v_cvt_pk_bf16_f32 v89, v84, v85
	global_store_dwordx4 v204, v[86:89], s[40:41] offset:256
	s_add_u32 s40, s38, 0x18000
	s_addc_u32 s41, s39, 0
	v_pk_mul_f32 v[78:79], v[78:79], v[186:187] op_sel_hi:[1,0]
	v_pk_mul_f32 v[80:81], v[80:81], v[186:187] op_sel_hi:[1,0]
	v_pk_mul_f32 v[74:75], v[74:75], v[186:187] op_sel_hi:[1,0]
	v_pk_mul_f32 v[76:77], v[76:77], v[186:187] op_sel_hi:[1,0]
	v_pk_fma_f32 v[78:79], v[130:131], v[78:79], v[162:163]
	v_pk_fma_f32 v[80:81], v[132:133], v[80:81], v[164:165]
	v_pk_fma_f32 v[74:75], v[134:135], v[74:75], v[166:167]
	v_pk_fma_f32 v[76:77], v[136:137], v[76:77], v[168:169]
	v_cvt_pk_bf16_f32 v78, v78, v79
	v_cvt_pk_bf16_f32 v79, v80, v81
	v_cvt_pk_bf16_f32 v80, v74, v75
	v_cvt_pk_bf16_f32 v81, v76, v77
	global_store_dwordx4 v204, v[78:81], s[40:41]
	v_pk_mul_f32 v[70:71], v[70:71], v[186:187] op_sel_hi:[1,0]
	v_pk_mul_f32 v[72:73], v[72:73], v[186:187] op_sel_hi:[1,0]
	v_pk_mul_f32 v[66:67], v[66:67], v[186:187] op_sel_hi:[1,0]
	v_pk_mul_f32 v[68:69], v[68:69], v[186:187] op_sel_hi:[1,0]
	v_pk_fma_f32 v[70:71], v[138:139], v[70:71], v[170:171]
	v_pk_fma_f32 v[72:73], v[140:141], v[72:73], v[172:173]
	v_pk_fma_f32 v[66:67], v[142:143], v[66:67], v[174:175]
	v_pk_fma_f32 v[68:69], v[144:145], v[68:69], v[176:177]
	v_cvt_pk_bf16_f32 v70, v70, v71
	v_cvt_pk_bf16_f32 v71, v72, v73
; __device__ __forceinline__ unsigned pk2(float lo, float hi) { f32x2_t v = {lo, hi}; bf16x2_t b = __builtin_convertvector(v, bf16x2_t); return __builtin_bit_cast(unsigned, b); }
; __device__ __forceinline__ void fused_norm_tail(CA& A, int l, int s) {
;     ...
; #pragma unroll
;     for (int r = 0; r < 32; ++r) {
;         const int row = u.pm * 256 + wave * 32 + r;
;         const float rstd = __builtin_bit_cast(float, __builtin_amdgcn_readlane(__builtin_bit_cast(int, rstd_l), r));
;         const f32x4 y = hrow[r] * rstd * ca + cb;
;         v2u o; o.x = pk2(y.x, y.y); o.y = pk2(y.z, y.w);
;         *(v2u*)(xn + (size_t)row * DM + col) = o;
;     }
	v_cvt_pk_bf16_f32 v72, v66, v67
	v_cvt_pk_bf16_f32 v73, v68, v69
	global_store_dwordx4 v204, v[70:73], s[40:41] offset:256
	s_add_u32 s40, s38, 0x40000
	s_addc_u32 s41, s39, 0
	v_pk_mul_f32 v[62:63], v[62:63], v[188:189] op_sel_hi:[1,0]
	v_pk_mul_f32 v[64:65], v[64:65], v[188:189] op_sel_hi:[1,0]
	v_pk_mul_f32 v[58:59], v[58:59], v[188:189] op_sel_hi:[1,0]
	v_pk_mul_f32 v[60:61], v[60:61], v[188:189] op_sel_hi:[1,0]
	v_pk_fma_f32 v[62:63], v[130:131], v[62:63], v[162:163]
	v_pk_fma_f32 v[64:65], v[132:133], v[64:65], v[164:165]
	v_pk_fma_f32 v[58:59], v[134:135], v[58:59], v[166:167]
	v_pk_fma_f32 v[60:61], v[136:137], v[60:61], v[168:169]
	v_cvt_pk_bf16_f32 v62, v62, v63
	v_cvt_pk_bf16_f32 v63, v64, v65
	v_cvt_pk_bf16_f32 v64, v58, v59
	v_cvt_pk_bf16_f32 v65, v60, v61
	global_store_dwordx4 v204, v[62:65], s[40:41]
	v_pk_mul_f32 v[54:55], v[54:55], v[188:189] op_sel_hi:[1,0]
	v_pk_mul_f32 v[56:57], v[56:57], v[188:189] op_sel_hi:[1,0]
	v_pk_mul_f32 v[50:51], v[50:51], v[188:189] op_sel_hi:[1,0]
	v_pk_mul_f32 v[52:53], v[52:53], v[188:189] op_sel_hi:[1,0]
	v_pk_fma_f32 v[54:55], v[138:139], v[54:55], v[170:171]
	v_pk_fma_f32 v[56:57], v[140:141], v[56:57], v[172:173]
	v_pk_fma_f32 v[50:51], v[142:143], v[50:51], v[174:175]
	v_pk_fma_f32 v[52:53], v[144:145], v[52:53], v[176:177]
	v_cvt_pk_bf16_f32 v54, v54, v55
	v_cvt_pk_bf16_f32 v55, v56, v57
	v_cvt_pk_bf16_f32 v56, v50, v51
	v_cvt_pk_bf16_f32 v57, v52, v53
	global_store_dwordx4 v204, v[54:57], s[40:41] offset:256
	s_add_u32 s40, s38, 0x48000
	s_addc_u32 s41, s39, 0
	v_pk_mul_f32 v[46:47], v[46:47], v[190:191] op_sel_hi:[1,0]
	v_pk_mul_f32 v[48:49], v[48:49], v[190:191] op_sel_hi:[1,0]
	v_pk_mul_f32 v[42:43], v[42:43], v[190:191] op_sel_hi:[1,0]
	v_pk_mul_f32 v[44:45], v[44:45], v[190:191] op_sel_hi:[1,0]
	v_pk_fma_f32 v[46:47], v[130:131], v[46:47], v[162:163]
	v_pk_fma_f32 v[48:49], v[132:133], v[48:49], v[164:165]
	v_pk_fma_f32 v[42:43], v[134:135], v[42:43], v[166:167]
	v_pk_fma_f32 v[44:45], v[136:137], v[44:45], v[168:169]
	v_cvt_pk_bf16_f32 v46, v46, v47
	v_cvt_pk_bf16_f32 v47, v48, v49
	v_cvt_pk_bf16_f32 v48, v42, v43
	v_cvt_pk_bf16_f32 v49, v44, v45
	global_store_dwordx4 v204, v[46:49], s[40:41]
	v_pk_mul_f32 v[38:39], v[38:39], v[190:191] op_sel_hi:[1,0]
	v_pk_mul_f32 v[40:41], v[40:41], v[190:191] op_sel_hi:[1,0]
	v_pk_mul_f32 v[34:35], v[34:35], v[190:191] op_sel_hi:[1,0]
	v_pk_mul_f32 v[36:37], v[36:37], v[190:191] op_sel_hi:[1,0]
	v_pk_fma_f32 v[38:39], v[138:139], v[38:39], v[170:171]
	v_pk_fma_f32 v[40:41], v[140:141], v[40:41], v[172:173]
	v_pk_fma_f32 v[34:35], v[142:143], v[34:35], v[174:175]
	v_pk_fma_f32 v[36:37], v[144:145], v[36:37], v[176:177]
	v_cvt_pk_bf16_f32 v38, v38, v39
	v_cvt_pk_bf16_f32 v39, v40, v41
	v_cvt_pk_bf16_f32 v40, v34, v35
	v_cvt_pk_bf16_f32 v41, v36, v37
	global_store_dwordx4 v204, v[38:41], s[40:41] offset:256
	s_add_u32 s40, s38, 0x50000
	s_addc_u32 s41, s39, 0
	v_pk_mul_f32 v[30:31], v[30:31], v[192:193] op_sel_hi:[1,0]
	v_pk_mul_f32 v[32:33], v[32:33], v[192:193] op_sel_hi:[1,0]
	v_pk_mul_f32 v[26:27], v[26:27], v[192:193] op_sel_hi:[1,0]
	v_pk_mul_f32 v[28:29], v[28:29], v[192:193] op_sel_hi:[1,0]
	v_pk_fma_f32 v[30:31], v[130:131], v[30:31], v[162:163]
	v_pk_fma_f32 v[32:33], v[132:133], v[32:33], v[164:165]
	v_pk_fma_f32 v[26:27], v[134:135], v[26:27], v[166:167]
	v_pk_fma_f32 v[28:29], v[136:137], v[28:29], v[168:169]
	v_cvt_pk_bf16_f32 v30, v30, v31
	v_cvt_pk_bf16_f32 v31, v32, v33
	v_cvt_pk_bf16_f32 v32, v26, v27
	v_cvt_pk_bf16_f32 v33, v28, v29
	global_store_dwordx4 v204, v[30:33], s[40:41]
	v_pk_mul_f32 v[22:23], v[22:23], v[192:193] op_sel_hi:[1,0]
	v_pk_mul_f32 v[24:25], v[24:25], v[192:193] op_sel_hi:[1,0]
	v_pk_mul_f32 v[18:19], v[18:19], v[192:193] op_sel_hi:[1,0]
	v_pk_mul_f32 v[20:21], v[20:21], v[192:193] op_sel_hi:[1,0]
	v_pk_fma_f32 v[22:23], v[138:139], v[22:23], v[170:171]
	v_pk_fma_f32 v[24:25], v[140:141], v[24:25], v[172:173]
	v_pk_fma_f32 v[18:19], v[142:143], v[18:19], v[174:175]
	v_pk_fma_f32 v[20:21], v[144:145], v[20:21], v[176:177]
	v_cvt_pk_bf16_f32 v22, v22, v23
	v_cvt_pk_bf16_f32 v23, v24, v25
	v_cvt_pk_bf16_f32 v24, v18, v19
	v_cvt_pk_bf16_f32 v25, v20, v21
	global_store_dwordx4 v204, v[22:25], s[40:41] offset:256
	s_add_u32 s40, s38, 0x58000
	s_addc_u32 s41, s39, 0
	v_pk_mul_f32 v[14:15], v[14:15], v[194:195] op_sel_hi:[1,0]
	v_pk_mul_f32 v[16:17], v[16:17], v[194:195] op_sel_hi:[1,0]
	v_pk_mul_f32 v[10:11], v[10:11], v[194:195] op_sel_hi:[1,0]
	v_pk_mul_f32 v[12:13], v[12:13], v[194:195] op_sel_hi:[1,0]
	v_pk_fma_f32 v[14:15], v[130:131], v[14:15], v[162:163]
	v_pk_fma_f32 v[16:17], v[132:133], v[16:17], v[164:165]
	v_pk_fma_f32 v[10:11], v[134:135], v[10:11], v[166:167]
	v_pk_fma_f32 v[12:13], v[136:137], v[12:13], v[168:169]
	v_cvt_pk_bf16_f32 v14, v14, v15
	v_cvt_pk_bf16_f32 v15, v16, v17
	v_cvt_pk_bf16_f32 v16, v10, v11
	v_cvt_pk_bf16_f32 v17, v12, v13
	global_store_dwordx4 v204, v[14:17], s[40:41]
	v_pk_mul_f32 v[6:7], v[6:7], v[194:195] op_sel_hi:[1,0]
	v_pk_mul_f32 v[8:9], v[8:9], v[194:195] op_sel_hi:[1,0]
	v_pk_mul_f32 v[2:3], v[2:3], v[194:195] op_sel_hi:[1,0]
	v_pk_mul_f32 v[4:5], v[4:5], v[194:195] op_sel_hi:[1,0]
	v_pk_fma_f32 v[6:7], v[138:139], v[6:7], v[170:171]
	v_pk_fma_f32 v[8:9], v[140:141], v[8:9], v[172:173]
	v_pk_fma_f32 v[2:3], v[142:143], v[2:3], v[174:175]
	v_pk_fma_f32 v[4:5], v[144:145], v[4:5], v[176:177]
	v_cvt_pk_bf16_f32 v6, v6, v7
	v_cvt_pk_bf16_f32 v7, v8, v9
	v_cvt_pk_bf16_f32 v8, v2, v3
	v_cvt_pk_bf16_f32 v9, v4, v5
	global_store_dwordx4 v204, v[6:9], s[40:41] offset:256
